# P0-SPLIT3: 480 more conversion units deferred (whole GU1-L1, DN2-L1 tail, EVOUT) into the phase 1/3/11 idle slots, on top of v074
# speedup vs baseline: 1.0052x; 1.0021x over previous
.LBB0_282:
	s_or_b64 exec, exec, s[22:23]
	v_readlane_b32 s0, v249, 12
	v_readlane_b32 s1, v249, 13
	s_andn2_b64 vcc, exec, s[0:1]
	s_cbranch_vccnz .LBB0_391
	s_mov_b32 s100, s98
	s_movk_i32 s101, 0x209f
	s_mov_b32 s83, 0
	s_cmpk_lg_u32 s98, 0x100
	s_cbranch_scc1 .Lp0_pre
	s_movk_i32 s101, 4287

.LBB0_286:
	s_add_i32 s82, s82, s100
	s_cmp_gt_i32 s82, s101
	s_cbranch_scc1 .LBB0_391
	s_mov_b32 s2, s82
	s_cmp_eq_u32 s83, 0
	s_cbranch_scc0 .Lp0m_sub
	s_cmpk_lg_u32 s98, 0x100
	s_cbranch_scc1 .Lp0m_done
	s_cmpk_lt_i32 s82, 704
	s_cbranch_scc1 .Lp0m_done
	s_addk_i32 s2, 704
	s_cmpk_lt_i32 s82, 1056
	s_cbranch_scc1 .Lp0m_done
	s_addk_i32 s2, 2464
	s_cmpk_lt_i32 s82, 1184
	s_cbranch_scc1 .Lp0m_done
	s_addk_i32 s2, 128
	s_cmpk_lt_i32 s82, 1824
	s_cbranch_scc1 .Lp0m_done
	s_addk_i32 s2, 128
	s_cmpk_lt_i32 s82, 2112
	s_cbranch_scc1 .Lp0m_done
	s_addk_i32 s2, 640
	s_branch .Lp0m_done

.Lp0m_1:
	s_addk_i32 s2, 1792
	s_cmpk_lt_i32 s82, 640
	s_cbranch_scc1 .Lp0m_done
	s_addk_i32 s2, 3104
	s_branch .Lp0m_done
.Lp0m_3:
	s_addk_i32 s2, 2432
	s_cmpk_lt_i32 s82, 384
	s_cbranch_scc1 .Lp0m_done
	s_addk_i32 s2, 704
	s_cmpk_lt_i32 s82, 736
	s_cbranch_scc1 .Lp0m_done
	s_addk_i32 s2, -3168
	s_cmpk_lt_i32 s82, 1440
	s_cbranch_scc1 .Lp0m_done
	s_addk_i32 s2, 4256
	s_cmpk_lt_i32 s82, 1952
	s_cbranch_scc1 .Lp0m_done
	s_addk_i32 s2, -4416
	s_branch .Lp0m_done

.Lp0m_11:
	s_addk_i32 s2, 3872
	s_cmpk_lt_i32 s82, 352
	s_cbranch_scc1 .Lp0m_done
	s_addk_i32 s2, 128
	s_cmpk_lt_i32 s82, 480
	s_cbranch_scc1 .Lp0m_done
	s_addk_i32 s2, 640
	s_branch .Lp0m_done

.Lp0s_ph1:
	s_cmpk_lt_u32 s16, 0x80
	s_cbranch_scc1 .Lp0s_skip
	s_cmpk_ge_u32 s16, 0xc0
	s_cbranch_scc1 .Lp0s_skip
	s_sub_i32 s69, s16, 0x80
	s_movk_i32 s100, 0x40
	s_movk_i32 s101, 767
	s_branch .Lp0s_go
.Lp0s_ph3:
	s_cmpk_lt_u32 s16, 0x40
	s_cbranch_scc1 .Lp0s_skip
	s_sub_i32 s69, s16, 0x40
	s_movk_i32 s100, 0xc0
	s_movk_i32 s101, 1983
	s_branch .Lp0s_go

.Lp0s_ph11:
	s_cmpk_lt_u32 s16, 0x80
	s_cbranch_scc1 .Lp0s_skip
	s_sub_i32 s69, s16, 0x80
	s_movk_i32 s100, 0x80
	s_movk_i32 s101, 607
